# bprep QK-norm 8-lane reductions via DPP adds instead of ds_bpermute (on top of v66)
# speedup vs baseline: 1.0005x; 1.0005x over previous
; __device__ __forceinline__ void unpack8(v4u w, float (&f)[8]) { f[0] = bflo(w.x); f[1] = bfhi(w.x); f[2] = bflo(w.y); f[3] = bfhi(w.y); f[4] = bflo(w.z); f[5] = bfhi(w.z); f[6] = bflo(w.w); f[7] = bfhi(w.w); }
; __device__ __forceinline__ v4u packf8(const float (&f)[8]) { v4u w; w.x = pk2(f[0], f[1]); w.y = pk2(f[2], f[3]); w.z = pk2(f[4], f[5]); w.w = pk2(f[6], f[7]); return w; }
; __device__ __forceinline__ void bprep_item(const Params& P, LAS unsigned char* lds, int item, int tid, int lane, int wave) {
;     ...
;                 unpack8(wq_[hi], f); float ss = 0.f;
; #pragma unroll
;                 for (int i = 0; i < 8; ++i) ss += f[i] * f[i];
;                 ss += __shfl_xor(ss, 1); ss += __shfl_xor(ss, 2); ss += __shfl_xor(ss, 4);
;                 float rstd = __builtin_amdgcn_rsqf(ss * (1.0f / 64.0f) + 1e-6f);
; #pragma unroll
;                 for (int i = 0; i < 8; ++i) f[i] = f[i] * (rstd * 0.18033688011f) * qg[i];
;                 *(v4u*)(qdst + (qblk * 8 + h) * 4096 + piece) = xchg8x8(xs, lane, packf8(f));
;                 unpack8(wk_[hi], f); ss = 0.f;
; #pragma unroll
;                 for (int i = 0; i < 8; ++i) ss += f[i] * f[i];
;                 ss += __shfl_xor(ss, 1); ss += __shfl_xor(ss, 2); ss += __shfl_xor(ss, 4);
;                 rstd = __builtin_amdgcn_rsqf(ss * (1.0f / 64.0f) + 1e-6f);
; #pragma unroll
;                 for (int i = 0; i < 8; ++i) f[i] = f[i] * rstd * kg[i];
;             } else { f[0] = ck_[hi][0][0]; f[1] = ck_[hi][0][1]; f[2] = ck_[hi][0][2]; f[3] = ck_[hi][0][3]; f[4] = ck_[hi][1][0]; f[5] = ck_[hi][1][1]; f[6] = ck_[hi][1][2]; f[7] = ck_[hi][1][3]; }
;             *(v4u*)(kdst + (kvblk * 8 + h) * 4096 + piece) = xchg8x8(xs, lane, packf8(f));
.LBB0_521:
	s_and_b64 vcc, exec, s[4:5]
	s_mov_b64 s[56:57], -1
	s_cbranch_vccnz .LBB0_523
	s_waitcnt vmcnt(2)
	v_lshlrev_b32_e32 v194, 16, v98
	v_and_b32_e32 v195, 0xffff0000, v98
	v_and_b32_e32 v35, 64, v192
	v_lshlrev_b32_e32 v186, 16, v99
	v_and_b32_e32 v187, 0xffff0000, v99
	v_pk_mul_f32 v[196:197], v[194:195], v[194:195]
	v_xor_b32_e32 v34, 1, v192
	v_add_u32_e32 v193, 64, v35
	v_pk_mul_f32 v[188:189], v[186:187], v[186:187]
	v_add_f32_e32 v196, v196, v197
	v_cmp_lt_i32_e32 vcc, v34, v193
	v_lshlrev_b32_e32 v38, 16, v100
	v_and_b32_e32 v39, 0xffff0000, v100
	v_add_f32_e32 v188, v188, v196
	v_cndmask_b32_e32 v34, v192, v34, vcc
	v_pk_mul_f32 v[40:41], v[38:39], v[38:39]
	v_add_f32_e32 v188, v189, v188
	v_lshlrev_b32_e32 v208, 2, v34
	v_lshlrev_b32_e32 v34, 16, v101
	v_and_b32_e32 v35, 0xffff0000, v101
	v_add_f32_e32 v40, v40, v188
	v_pk_mul_f32 v[36:37], v[34:35], v[34:35]
	v_add_f32_e32 v40, v41, v40
	v_add_f32_e32 v36, v36, v40
	v_add_f32_e32 v36, v37, v36
	v_xor_b32_e32 v40, 2, v192
	v_cmp_lt_i32_e32 vcc, v40, v193
	s_waitcnt vmcnt(1)
	v_lshlrev_b32_e32 v200, 16, v94
	v_and_b32_e32 v201, 0xffff0000, v94
	v_cndmask_b32_e32 v40, v192, v40, vcc
	v_lshlrev_b32_e32 v209, 2, v40
	s_waitcnt lgkmcnt(0)
	v_add_f32_dpp v36, v36, v36 quad_perm:[1,0,3,2] row_mask:0xf bank_mask:0xf
	v_xor_b32_e32 v40, 4, v192
	v_cmp_lt_i32_e32 vcc, v40, v193
	v_pk_mul_f32 v[202:203], v[200:201], v[200:201]
	v_lshlrev_b32_e32 v204, 16, v95
	v_cndmask_b32_e32 v40, v192, v40, vcc
	v_lshlrev_b32_e32 v193, 2, v40
	s_waitcnt lgkmcnt(0)
	v_add_f32_dpp v36, v36, v36 quad_perm:[2,3,0,1] row_mask:0xf bank_mask:0xf
	v_and_b32_e32 v205, 0xffff0000, v95
	v_pk_mul_f32 v[206:207], v[204:205], v[204:205]
	v_and_b32_e32 v188, 0xffff0000, v96
	v_lshlrev_b32_e32 v189, 16, v96
	s_waitcnt lgkmcnt(0)
	v_add_f32_dpp v36, v36, v36 row_half_mirror row_mask:0xf bank_mask:0xf
	v_fmamk_f32 v36, v36, 0x3c800000, v171
	v_rsq_f32_e32 v36, v36
	v_and_b32_e32 v196, 0xffff0000, v97
	v_lshlrev_b32_e32 v197, 16, v97
	v_pk_mul_f32 v[198:199], v[196:197], v[196:197]
	v_mul_f32_e32 v36, 0x3e38aa3b, v36
	v_pk_mul_f32 v[40:41], v[36:37], v[194:195] op_sel_hi:[0,1]
	v_pk_mul_f32 v[186:187], v[36:37], v[186:187] op_sel_hi:[0,1]
	v_add_f32_e32 v37, v202, v203
	v_add_f32_e32 v37, v206, v37
	v_pk_mul_f32 v[194:195], v[188:189], v[188:189]
	v_add_f32_e32 v37, v207, v37
	v_add_f32_e32 v37, v195, v37
	v_add_f32_e32 v37, v194, v37
	v_add_f32_e32 v37, v199, v37
	v_add_f32_e32 v37, v198, v37
	v_pk_mul_f32 v[38:39], v[36:37], v[38:39] op_sel_hi:[0,1]
	v_pk_mul_f32 v[34:35], v[36:37], v[34:35] op_sel_hi:[0,1]
	v_pk_mul_f32 v[38:39], v[42:43], v[38:39]
	v_pk_mul_f32 v[40:41], v[46:47], v[40:41]
	s_waitcnt lgkmcnt(0)
	v_add_f32_dpp v37, v37, v37 quad_perm:[1,0,3,2] row_mask:0xf bank_mask:0xf
	v_cvt_pk_bf16_f32 v36, v38, v39
	v_pk_mul_f32 v[186:187], v[48:49], v[186:187]
	v_pk_mul_f32 v[194:195], v[44:45], v[34:35]
	v_cvt_pk_bf16_f32 v34, v40, v41
	s_waitcnt lgkmcnt(0)
	v_add_f32_dpp v38, v37, v37 quad_perm:[2,3,0,1] row_mask:0xf bank_mask:0xf
	v_cvt_pk_bf16_f32 v35, v186, v187
	v_cvt_pk_bf16_f32 v37, v194, v195
	ds_write_b128 v190, v[34:37]
	ds_read_b128 v[34:37], v191
	s_waitcnt lgkmcnt(2)
	v_add_f32_dpp v38, v38, v38 row_half_mirror row_mask:0xf bank_mask:0xf
	v_fmamk_f32 v38, v38, 0x3c800000, v171
	v_rsq_f32_e32 v186, v38
	s_lshl_b32 s18, s8, 12
	s_mov_b32 s19, s9
	v_lshl_add_u64 v[38:39], v[180:181], 0, s[18:19]
	s_waitcnt lgkmcnt(0)
	global_store_dwordx4 v[38:39], v[34:37], off nt
	s_nop 1
	v_pk_mul_f32 v[34:35], v[186:187], v[200:201] op_sel_hi:[0,1]
	s_waitcnt vmcnt(1)
	v_pk_mul_f32 v[38:39], v[54:55], v[34:35]
	v_pk_mul_f32 v[34:35], v[186:187], v[204:205] op_sel_hi:[0,1]
	v_pk_mul_f32 v[40:41], v[56:57], v[34:35]
	v_pk_mul_f32 v[34:35], v[186:187], v[188:189] op_sel_hi:[0,1]
	v_pk_mul_f32 v[36:37], v[186:187], v[196:197] op_sel_hi:[0,1]
	v_pk_mul_f32 v[34:35], v[50:51], v[34:35] op_sel:[0,1] op_sel_hi:[1,0]
	v_pk_mul_f32 v[36:37], v[52:53], v[36:37] op_sel:[0,1] op_sel_hi:[1,0]
	s_cbranch_execz .LBB0_524
	s_branch .LBB0_525

; __device__ __forceinline__ void bprep_item(const Params& P, LAS unsigned char* lds, int item, int tid, int lane, int wave) {
;     ...
;                 unpack8(wq_[hi], f); float ss = 0.f;
; #pragma unroll
;                 for (int i = 0; i < 8; ++i) ss += f[i] * f[i];
;                 ss += __shfl_xor(ss, 1); ss += __shfl_xor(ss, 2); ss += __shfl_xor(ss, 4);
;                 float rstd = __builtin_amdgcn_rsqf(ss * (1.0f / 64.0f) + 1e-6f);
; #pragma unroll
;                 for (int i = 0; i < 8; ++i) f[i] = f[i] * (rstd * 0.18033688011f) * qg[i];
;                 *(v4u*)(qdst + (qblk * 8 + h) * 4096 + piece) = xchg8x8(xs, lane, packf8(f));
;                 unpack8(wk_[hi], f); ss = 0.f;
; #pragma unroll
;                 for (int i = 0; i < 8; ++i) ss += f[i] * f[i];
;                 ss += __shfl_xor(ss, 1); ss += __shfl_xor(ss, 2); ss += __shfl_xor(ss, 4);
;                 rstd = __builtin_amdgcn_rsqf(ss * (1.0f / 64.0f) + 1e-6f);
; #pragma unroll
;                 for (int i = 0; i < 8; ++i) f[i] = f[i] * rstd * kg[i];
;             } else { f[0] = ck_[hi][0][0]; f[1] = ck_[hi][0][1]; f[2] = ck_[hi][0][2]; f[3] = ck_[hi][0][3]; f[4] = ck_[hi][1][0]; f[5] = ck_[hi][1][1]; f[6] = ck_[hi][1][2]; f[7] = ck_[hi][1][3]; }
;             *(v4u*)(kdst + (kvblk * 8 + h) * 4096 + piece) = xchg8x8(xs, lane, packf8(f));
;             {
;                 float* ko = nullptr;
;                 if (mode == 0) { const int ts = c * 64 + tl; if (ts >= TP - 512) ko = P.out + O_KP + (((size_t)s * 512 + (ts - (TP - 512))) * 8 + h) * 64 + 8 * part; }
;                 else if (mode == 1 && valid) ko = P.out + O_KS + (((size_t)s * 16 + tl) * 8 + h) * 64 + 8 * part;
;                 if (ko) { ((f32x4*)ko)[0] = (f32x4){f[0], f[1], f[2], f[3]}; ((f32x4*)ko)[1] = (f32x4){f[4], f[5], f[6], f[7]}; }
;             }
;             if (mode != 2) unpack8(wv_[hi], f);
;             else { f[0] = cv_[hi][0][0]; f[1] = cv_[hi][0][1]; f[2] = cv_[hi][0][2]; f[3] = cv_[hi][0][3]; f[4] = cv_[hi][1][0]; f[5] = cv_[hi][1][1]; f[6] = cv_[hi][1][2]; f[7] = cv_[hi][1][3]; }
;             {
;                 float* vo = nullptr;
;                 if (mode == 0) { const int ts = c * 64 + tl; if (ts >= TP - 512) vo = P.out + O_VP + (((size_t)s * 512 + (ts - (TP - 512))) * 8 + h) * 64 + 8 * part; }
.LBB0_532:
	s_or_b64 exec, exec, s[56:57]
	v_cvt_pk_bf16_f32 v34, v34, v35
	v_cvt_pk_bf16_f32 v35, v36, v37
	v_cvt_pk_bf16_f32 v36, v38, v39
	v_lshl_add_u32 v38, s8, 6, v138
	v_cvt_pk_bf16_f32 v37, v40, v41
	v_mad_u64_u32 v[38:39], s[18:19], v38, s58, v[158:159]
	s_and_b64 vcc, exec, s[4:5]
	s_mov_b64 s[56:57], -1
	ds_write_b128 v38, v[34:37]
	s_cbranch_vccnz .LBB0_534
	v_lshlrev_b32_e32 v194, 16, v110
	v_and_b32_e32 v195, 0xffff0000, v110
	v_and_b32_e32 v35, 64, v192
	v_lshlrev_b32_e32 v186, 16, v111
	v_and_b32_e32 v187, 0xffff0000, v111
	v_pk_mul_f32 v[196:197], v[194:195], v[194:195]
	v_xor_b32_e32 v34, 1, v192
	v_add_u32_e32 v193, 64, v35
	v_pk_mul_f32 v[188:189], v[186:187], v[186:187]
	v_add_f32_e32 v196, v196, v197
	v_cmp_lt_i32_e32 vcc, v34, v193
	v_lshlrev_b32_e32 v38, 16, v112
	v_and_b32_e32 v39, 0xffff0000, v112
	v_add_f32_e32 v188, v188, v196
	v_cndmask_b32_e32 v34, v192, v34, vcc
	v_pk_mul_f32 v[40:41], v[38:39], v[38:39]
	v_add_f32_e32 v188, v189, v188
	v_lshlrev_b32_e32 v208, 2, v34
	v_lshlrev_b32_e32 v34, 16, v113
	v_and_b32_e32 v35, 0xffff0000, v113
	v_add_f32_e32 v40, v40, v188
	v_pk_mul_f32 v[36:37], v[34:35], v[34:35]
	v_add_f32_e32 v40, v41, v40
	v_add_f32_e32 v36, v36, v40
	v_add_f32_e32 v36, v37, v36
	v_xor_b32_e32 v40, 2, v192
	v_cmp_lt_i32_e32 vcc, v40, v193
	v_lshlrev_b32_e32 v200, 16, v106
	v_and_b32_e32 v201, 0xffff0000, v106
	v_cndmask_b32_e32 v40, v192, v40, vcc
	v_lshlrev_b32_e32 v209, 2, v40
	s_waitcnt lgkmcnt(0)
	v_add_f32_dpp v36, v36, v36 quad_perm:[1,0,3,2] row_mask:0xf bank_mask:0xf
	v_xor_b32_e32 v40, 4, v192
	v_cmp_lt_i32_e32 vcc, v40, v193
	v_pk_mul_f32 v[202:203], v[200:201], v[200:201]
	v_lshlrev_b32_e32 v204, 16, v107
	v_cndmask_b32_e32 v40, v192, v40, vcc
	v_lshlrev_b32_e32 v193, 2, v40
	s_waitcnt lgkmcnt(0)
	v_add_f32_dpp v36, v36, v36 quad_perm:[2,3,0,1] row_mask:0xf bank_mask:0xf
	v_and_b32_e32 v205, 0xffff0000, v107
	v_pk_mul_f32 v[206:207], v[204:205], v[204:205]
	v_and_b32_e32 v188, 0xffff0000, v108
	v_lshlrev_b32_e32 v189, 16, v108
	s_waitcnt lgkmcnt(0)
	v_add_f32_dpp v36, v36, v36 row_half_mirror row_mask:0xf bank_mask:0xf
	v_fmamk_f32 v36, v36, 0x3c800000, v171
	v_rsq_f32_e32 v36, v36
	v_and_b32_e32 v196, 0xffff0000, v109
	v_lshlrev_b32_e32 v197, 16, v109
	v_pk_mul_f32 v[198:199], v[196:197], v[196:197]
	v_mul_f32_e32 v36, 0x3e38aa3b, v36
	v_pk_mul_f32 v[40:41], v[36:37], v[194:195] op_sel_hi:[0,1]
	v_add_f32_e32 v37, v202, v203
	v_add_f32_e32 v37, v206, v37
	v_pk_mul_f32 v[194:195], v[188:189], v[188:189]
	v_add_f32_e32 v37, v207, v37
	v_add_f32_e32 v37, v195, v37
	v_add_f32_e32 v37, v194, v37
	v_add_f32_e32 v37, v199, v37
	v_add_f32_e32 v37, v198, v37
	v_pk_mul_f32 v[186:187], v[36:37], v[186:187] op_sel_hi:[0,1]
	v_pk_mul_f32 v[38:39], v[36:37], v[38:39] op_sel_hi:[0,1]
	v_pk_mul_f32 v[40:41], v[46:47], v[40:41]
	v_pk_mul_f32 v[186:187], v[48:49], v[186:187]
	s_waitcnt lgkmcnt(0)
	v_add_f32_dpp v37, v37, v37 quad_perm:[1,0,3,2] row_mask:0xf bank_mask:0xf
	v_pk_mul_f32 v[34:35], v[36:37], v[34:35] op_sel_hi:[0,1]
	v_pk_mul_f32 v[194:195], v[44:45], v[34:35]
	v_cvt_pk_bf16_f32 v34, v40, v41
	v_pk_mul_f32 v[38:39], v[42:43], v[38:39]
	s_waitcnt lgkmcnt(0)
	v_add_f32_dpp v40, v37, v37 quad_perm:[2,3,0,1] row_mask:0xf bank_mask:0xf
	v_cvt_pk_bf16_f32 v35, v186, v187
	v_cvt_pk_bf16_f32 v36, v38, v39
	v_cvt_pk_bf16_f32 v37, v194, v195
	ds_write_b128 v190, v[34:37]
	s_waitcnt lgkmcnt(1)
	v_add_f32_dpp v38, v40, v40 row_half_mirror row_mask:0xf bank_mask:0xf
	ds_read_b128 v[34:37], v191
	v_fmamk_f32 v38, v38, 0x3c800000, v171
	v_rsq_f32_e32 v186, v38
	s_lshl_b32 s8, s52, 12
	v_lshl_add_u64 v[38:39], v[180:181], 0, s[8:9]
	s_waitcnt lgkmcnt(0)
	global_store_dwordx4 v[38:39], v[34:37], off nt
	s_mov_b64 s[56:57], 0
	s_nop 0
	v_pk_mul_f32 v[34:35], v[186:187], v[200:201] op_sel_hi:[0,1]
	v_pk_mul_f32 v[38:39], v[54:55], v[34:35]
	v_pk_mul_f32 v[34:35], v[186:187], v[204:205] op_sel_hi:[0,1]
	v_pk_mul_f32 v[40:41], v[56:57], v[34:35]
	v_pk_mul_f32 v[34:35], v[186:187], v[188:189] op_sel_hi:[0,1]
	v_pk_mul_f32 v[36:37], v[186:187], v[196:197] op_sel_hi:[0,1]
	v_pk_mul_f32 v[34:35], v[50:51], v[34:35] op_sel:[0,1] op_sel_hi:[1,0]
	v_pk_mul_f32 v[36:37], v[52:53], v[36:37] op_sel:[0,1] op_sel_hi:[1,0]

; __device__ __forceinline__ void bprep_item(const Params& P, LAS unsigned char* lds, int item, int tid, int lane, int wave) {
;     ...
;                 unpack8(wq_[hi], f); float ss = 0.f;
; #pragma unroll
;                 for (int i = 0; i < 8; ++i) ss += f[i] * f[i];
;                 ss += __shfl_xor(ss, 1); ss += __shfl_xor(ss, 2); ss += __shfl_xor(ss, 4);
;                 float rstd = __builtin_amdgcn_rsqf(ss * (1.0f / 64.0f) + 1e-6f);
; #pragma unroll
;                 for (int i = 0; i < 8; ++i) f[i] = f[i] * (rstd * 0.18033688011f) * qg[i];
;                 *(v4u*)(qdst + (qblk * 8 + h) * 4096 + piece) = xchg8x8(xs, lane, packf8(f));
;                 unpack8(wk_[hi], f); ss = 0.f;
; #pragma unroll
;                 for (int i = 0; i < 8; ++i) ss += f[i] * f[i];
;                 ss += __shfl_xor(ss, 1); ss += __shfl_xor(ss, 2); ss += __shfl_xor(ss, 4);
;                 rstd = __builtin_amdgcn_rsqf(ss * (1.0f / 64.0f) + 1e-6f);
; #pragma unroll
;                 for (int i = 0; i < 8; ++i) f[i] = f[i] * rstd * kg[i];
;             } else { f[0] = ck_[hi][0][0]; f[1] = ck_[hi][0][1]; f[2] = ck_[hi][0][2]; f[3] = ck_[hi][0][3]; f[4] = ck_[hi][1][0]; f[5] = ck_[hi][1][1]; f[6] = ck_[hi][1][2]; f[7] = ck_[hi][1][3]; }
;             *(v4u*)(kdst + (kvblk * 8 + h) * 4096 + piece) = xchg8x8(xs, lane, packf8(f));
;             {
;                 float* ko = nullptr;
;                 if (mode == 0) { const int ts = c * 64 + tl; if (ts >= TP - 512) ko = P.out + O_KP + (((size_t)s * 512 + (ts - (TP - 512))) * 8 + h) * 64 + 8 * part; }
;                 else if (mode == 1 && valid) ko = P.out + O_KS + (((size_t)s * 16 + tl) * 8 + h) * 64 + 8 * part;
;                 if (ko) { ((f32x4*)ko)[0] = (f32x4){f[0], f[1], f[2], f[3]}; ((f32x4*)ko)[1] = (f32x4){f[4], f[5], f[6], f[7]}; }
;             }
;             if (mode != 2) unpack8(wv_[hi], f);
;             else { f[0] = cv_[hi][0][0]; f[1] = cv_[hi][0][1]; f[2] = cv_[hi][0][2]; f[3] = cv_[hi][0][3]; f[4] = cv_[hi][1][0]; f[5] = cv_[hi][1][1]; f[6] = cv_[hi][1][2]; f[7] = cv_[hi][1][3]; }
;             {
;                 float* vo = nullptr;
;                 if (mode == 0) { const int ts = c * 64 + tl; if (ts >= TP - 512) vo = P.out + O_VP + (((size_t)s * 512 + (ts - (TP - 512))) * 8 + h) * 64 + 8 * part; }
.LBB0_543:
	s_or_b64 exec, exec, s[56:57]
	v_cvt_pk_bf16_f32 v34, v34, v35
	v_cvt_pk_bf16_f32 v35, v36, v37
	v_cvt_pk_bf16_f32 v36, v38, v39
	v_lshl_add_u32 v38, s52, 6, v138
	v_cvt_pk_bf16_f32 v37, v40, v41
	v_mad_u64_u32 v[38:39], s[18:19], v38, s58, v[158:159]
	s_and_b64 vcc, exec, s[4:5]
	s_mov_b64 s[52:53], -1
	ds_write_b128 v38, v[34:37]
	s_cbranch_vccnz .LBB0_545
	v_lshlrev_b32_e32 v194, 16, v122
	v_and_b32_e32 v195, 0xffff0000, v122
	v_and_b32_e32 v35, 64, v192
	v_lshlrev_b32_e32 v186, 16, v123
	v_and_b32_e32 v187, 0xffff0000, v123
	v_pk_mul_f32 v[196:197], v[194:195], v[194:195]
	v_xor_b32_e32 v34, 1, v192
	v_add_u32_e32 v193, 64, v35
	v_pk_mul_f32 v[188:189], v[186:187], v[186:187]
	v_add_f32_e32 v196, v196, v197
	v_cmp_lt_i32_e32 vcc, v34, v193
	v_lshlrev_b32_e32 v38, 16, v124
	v_and_b32_e32 v39, 0xffff0000, v124
	v_add_f32_e32 v188, v188, v196
	v_cndmask_b32_e32 v34, v192, v34, vcc
	v_pk_mul_f32 v[40:41], v[38:39], v[38:39]
	v_add_f32_e32 v188, v189, v188
	v_lshlrev_b32_e32 v208, 2, v34
	v_lshlrev_b32_e32 v34, 16, v125
	v_and_b32_e32 v35, 0xffff0000, v125
	v_add_f32_e32 v40, v40, v188
	v_pk_mul_f32 v[36:37], v[34:35], v[34:35]
	v_add_f32_e32 v40, v41, v40
	v_add_f32_e32 v36, v36, v40
	v_add_f32_e32 v36, v37, v36
	v_xor_b32_e32 v40, 2, v192
	v_cmp_lt_i32_e32 vcc, v40, v193
	v_lshlrev_b32_e32 v200, 16, v118
	v_and_b32_e32 v201, 0xffff0000, v118
	v_cndmask_b32_e32 v40, v192, v40, vcc
	v_lshlrev_b32_e32 v209, 2, v40
	s_waitcnt lgkmcnt(0)
	v_add_f32_dpp v36, v36, v36 quad_perm:[1,0,3,2] row_mask:0xf bank_mask:0xf
	v_xor_b32_e32 v40, 4, v192
	v_cmp_lt_i32_e32 vcc, v40, v193
	v_pk_mul_f32 v[202:203], v[200:201], v[200:201]
	v_lshlrev_b32_e32 v204, 16, v119
	v_cndmask_b32_e32 v40, v192, v40, vcc
	v_lshlrev_b32_e32 v193, 2, v40
	s_waitcnt lgkmcnt(0)
	v_add_f32_dpp v36, v36, v36 quad_perm:[2,3,0,1] row_mask:0xf bank_mask:0xf
	v_and_b32_e32 v205, 0xffff0000, v119
	v_pk_mul_f32 v[206:207], v[204:205], v[204:205]
	v_and_b32_e32 v188, 0xffff0000, v120
	v_lshlrev_b32_e32 v189, 16, v120
	s_waitcnt lgkmcnt(0)
	v_add_f32_dpp v36, v36, v36 row_half_mirror row_mask:0xf bank_mask:0xf
	v_fmamk_f32 v36, v36, 0x3c800000, v171
	v_rsq_f32_e32 v36, v36
	v_and_b32_e32 v196, 0xffff0000, v121
	v_lshlrev_b32_e32 v197, 16, v121
	v_pk_mul_f32 v[198:199], v[196:197], v[196:197]
	v_mul_f32_e32 v36, 0x3e38aa3b, v36
	v_pk_mul_f32 v[40:41], v[36:37], v[194:195] op_sel_hi:[0,1]
	v_add_f32_e32 v37, v202, v203
	v_add_f32_e32 v37, v206, v37
	v_pk_mul_f32 v[194:195], v[188:189], v[188:189]
	v_add_f32_e32 v37, v207, v37
	v_add_f32_e32 v37, v195, v37
	v_add_f32_e32 v37, v194, v37
	v_add_f32_e32 v37, v199, v37
	v_add_f32_e32 v37, v198, v37
	v_pk_mul_f32 v[186:187], v[36:37], v[186:187] op_sel_hi:[0,1]
	v_pk_mul_f32 v[38:39], v[36:37], v[38:39] op_sel_hi:[0,1]
	v_pk_mul_f32 v[40:41], v[46:47], v[40:41]
	v_pk_mul_f32 v[186:187], v[48:49], v[186:187]
	s_waitcnt lgkmcnt(0)
	v_add_f32_dpp v37, v37, v37 quad_perm:[1,0,3,2] row_mask:0xf bank_mask:0xf
	v_pk_mul_f32 v[34:35], v[36:37], v[34:35] op_sel_hi:[0,1]
	v_pk_mul_f32 v[194:195], v[44:45], v[34:35]
	v_cvt_pk_bf16_f32 v34, v40, v41
	v_pk_mul_f32 v[38:39], v[42:43], v[38:39]
	s_waitcnt lgkmcnt(0)
	v_add_f32_dpp v40, v37, v37 quad_perm:[2,3,0,1] row_mask:0xf bank_mask:0xf
	v_cvt_pk_bf16_f32 v35, v186, v187
	v_cvt_pk_bf16_f32 v36, v38, v39
	v_cvt_pk_bf16_f32 v37, v194, v195
	ds_write_b128 v190, v[34:37]
	s_waitcnt lgkmcnt(1)
	v_add_f32_dpp v38, v40, v40 row_half_mirror row_mask:0xf bank_mask:0xf
	ds_read_b128 v[34:37], v191
	v_fmamk_f32 v38, v38, 0x3c800000, v171
	v_rsq_f32_e32 v186, v38
	s_lshl_b32 s8, s48, 12
	v_lshl_add_u64 v[38:39], v[180:181], 0, s[8:9]
	s_waitcnt lgkmcnt(0)
	global_store_dwordx4 v[38:39], v[34:37], off nt
	s_mov_b64 s[52:53], 0
	s_nop 0
	v_pk_mul_f32 v[34:35], v[186:187], v[200:201] op_sel_hi:[0,1]
	v_pk_mul_f32 v[38:39], v[54:55], v[34:35]
	v_pk_mul_f32 v[34:35], v[186:187], v[204:205] op_sel_hi:[0,1]
	v_pk_mul_f32 v[40:41], v[56:57], v[34:35]
	v_pk_mul_f32 v[34:35], v[186:187], v[188:189] op_sel_hi:[0,1]
	v_pk_mul_f32 v[36:37], v[186:187], v[196:197] op_sel_hi:[0,1]
	v_pk_mul_f32 v[34:35], v[50:51], v[34:35] op_sel:[0,1] op_sel_hi:[1,0]
	v_pk_mul_f32 v[36:37], v[52:53], v[36:37] op_sel:[0,1] op_sel_hi:[1,0]

; __device__ __forceinline__ void bprep_item(const Params& P, LAS unsigned char* lds, int item, int tid, int lane, int wave) {
;     ...
;                 unpack8(wq_[hi], f); float ss = 0.f;
; #pragma unroll
;                 for (int i = 0; i < 8; ++i) ss += f[i] * f[i];
;                 ss += __shfl_xor(ss, 1); ss += __shfl_xor(ss, 2); ss += __shfl_xor(ss, 4);
;                 float rstd = __builtin_amdgcn_rsqf(ss * (1.0f / 64.0f) + 1e-6f);
; #pragma unroll
;                 for (int i = 0; i < 8; ++i) f[i] = f[i] * (rstd * 0.18033688011f) * qg[i];
;                 *(v4u*)(qdst + (qblk * 8 + h) * 4096 + piece) = xchg8x8(xs, lane, packf8(f));
;                 unpack8(wk_[hi], f); ss = 0.f;
; #pragma unroll
;                 for (int i = 0; i < 8; ++i) ss += f[i] * f[i];
;                 ss += __shfl_xor(ss, 1); ss += __shfl_xor(ss, 2); ss += __shfl_xor(ss, 4);
;                 rstd = __builtin_amdgcn_rsqf(ss * (1.0f / 64.0f) + 1e-6f);
; #pragma unroll
;                 for (int i = 0; i < 8; ++i) f[i] = f[i] * rstd * kg[i];
;             } else { f[0] = ck_[hi][0][0]; f[1] = ck_[hi][0][1]; f[2] = ck_[hi][0][2]; f[3] = ck_[hi][0][3]; f[4] = ck_[hi][1][0]; f[5] = ck_[hi][1][1]; f[6] = ck_[hi][1][2]; f[7] = ck_[hi][1][3]; }
;             *(v4u*)(kdst + (kvblk * 8 + h) * 4096 + piece) = xchg8x8(xs, lane, packf8(f));
;             {
;                 float* ko = nullptr;
;                 if (mode == 0) { const int ts = c * 64 + tl; if (ts >= TP - 512) ko = P.out + O_KP + (((size_t)s * 512 + (ts - (TP - 512))) * 8 + h) * 64 + 8 * part; }
;                 else if (mode == 1 && valid) ko = P.out + O_KS + (((size_t)s * 16 + tl) * 8 + h) * 64 + 8 * part;
;                 if (ko) { ((f32x4*)ko)[0] = (f32x4){f[0], f[1], f[2], f[3]}; ((f32x4*)ko)[1] = (f32x4){f[4], f[5], f[6], f[7]}; }
;             }
;             if (mode != 2) unpack8(wv_[hi], f);
;             else { f[0] = cv_[hi][0][0]; f[1] = cv_[hi][0][1]; f[2] = cv_[hi][0][2]; f[3] = cv_[hi][0][3]; f[4] = cv_[hi][1][0]; f[5] = cv_[hi][1][1]; f[6] = cv_[hi][1][2]; f[7] = cv_[hi][1][3]; }
;             {
;                 float* vo = nullptr;
;                 if (mode == 0) { const int ts = c * 64 + tl; if (ts >= TP - 512) vo = P.out + O_VP + (((size_t)s * 512 + (ts - (TP - 512))) * 8 + h) * 64 + 8 * part; }
.LBB0_554:
	s_or_b64 exec, exec, s[52:53]
	v_cvt_pk_bf16_f32 v34, v34, v35
	v_cvt_pk_bf16_f32 v35, v36, v37
	v_cvt_pk_bf16_f32 v36, v38, v39
	v_lshl_add_u32 v38, s48, 6, v138
	v_cvt_pk_bf16_f32 v37, v40, v41
	v_mad_u64_u32 v[38:39], s[18:19], v38, s58, v[158:159]
	s_and_b64 vcc, exec, s[4:5]
	s_mov_b64 s[48:49], -1
	ds_write_b128 v38, v[34:37]
	s_cbranch_vccnz .LBB0_556
	v_lshlrev_b32_e32 v194, 16, v134
	v_and_b32_e32 v195, 0xffff0000, v134
	v_and_b32_e32 v35, 64, v192
	v_lshlrev_b32_e32 v186, 16, v135
	v_and_b32_e32 v187, 0xffff0000, v135
	v_pk_mul_f32 v[196:197], v[194:195], v[194:195]
	v_xor_b32_e32 v34, 1, v192
	v_add_u32_e32 v193, 64, v35
	v_pk_mul_f32 v[188:189], v[186:187], v[186:187]
	v_add_f32_e32 v196, v196, v197
	v_cmp_lt_i32_e32 vcc, v34, v193
	v_lshlrev_b32_e32 v38, 16, v136
	v_and_b32_e32 v39, 0xffff0000, v136
	v_add_f32_e32 v188, v188, v196
	v_cndmask_b32_e32 v34, v192, v34, vcc
	v_pk_mul_f32 v[40:41], v[38:39], v[38:39]
	v_add_f32_e32 v188, v189, v188
	v_lshlrev_b32_e32 v208, 2, v34
	v_lshlrev_b32_e32 v34, 16, v137
	v_and_b32_e32 v35, 0xffff0000, v137
	v_add_f32_e32 v40, v40, v188
	v_pk_mul_f32 v[36:37], v[34:35], v[34:35]
	v_add_f32_e32 v40, v41, v40
	v_add_f32_e32 v36, v36, v40
	v_add_f32_e32 v36, v37, v36
	v_xor_b32_e32 v40, 2, v192
	v_cmp_lt_i32_e32 vcc, v40, v193
	v_lshlrev_b32_e32 v200, 16, v130
	v_and_b32_e32 v201, 0xffff0000, v130
	v_cndmask_b32_e32 v40, v192, v40, vcc
	v_lshlrev_b32_e32 v209, 2, v40
	s_waitcnt lgkmcnt(0)
	v_add_f32_dpp v36, v36, v36 quad_perm:[1,0,3,2] row_mask:0xf bank_mask:0xf
	v_xor_b32_e32 v40, 4, v192
	v_cmp_lt_i32_e32 vcc, v40, v193
	v_pk_mul_f32 v[202:203], v[200:201], v[200:201]
	v_lshlrev_b32_e32 v204, 16, v131
	v_cndmask_b32_e32 v40, v192, v40, vcc
	v_lshlrev_b32_e32 v193, 2, v40
	s_waitcnt lgkmcnt(0)
	v_add_f32_dpp v36, v36, v36 quad_perm:[2,3,0,1] row_mask:0xf bank_mask:0xf
	v_and_b32_e32 v205, 0xffff0000, v131
	v_pk_mul_f32 v[206:207], v[204:205], v[204:205]
	v_and_b32_e32 v188, 0xffff0000, v132
	v_lshlrev_b32_e32 v189, 16, v132
	s_waitcnt lgkmcnt(0)
	v_add_f32_dpp v36, v36, v36 row_half_mirror row_mask:0xf bank_mask:0xf
	v_fmamk_f32 v36, v36, 0x3c800000, v171
	v_rsq_f32_e32 v36, v36
	v_and_b32_e32 v196, 0xffff0000, v133
	v_lshlrev_b32_e32 v197, 16, v133
	v_pk_mul_f32 v[198:199], v[196:197], v[196:197]
	v_mul_f32_e32 v36, 0x3e38aa3b, v36
	v_pk_mul_f32 v[40:41], v[36:37], v[194:195] op_sel_hi:[0,1]
	v_add_f32_e32 v37, v202, v203
	v_add_f32_e32 v37, v206, v37
	v_pk_mul_f32 v[194:195], v[188:189], v[188:189]
	v_add_f32_e32 v37, v207, v37
	v_add_f32_e32 v37, v195, v37
	v_add_f32_e32 v37, v194, v37
	v_add_f32_e32 v37, v199, v37
	v_add_f32_e32 v37, v198, v37
	v_pk_mul_f32 v[186:187], v[36:37], v[186:187] op_sel_hi:[0,1]
	v_pk_mul_f32 v[38:39], v[36:37], v[38:39] op_sel_hi:[0,1]
	v_pk_mul_f32 v[40:41], v[46:47], v[40:41]
	v_pk_mul_f32 v[186:187], v[48:49], v[186:187]
	s_waitcnt lgkmcnt(0)
	v_add_f32_dpp v37, v37, v37 quad_perm:[1,0,3,2] row_mask:0xf bank_mask:0xf
	v_pk_mul_f32 v[34:35], v[36:37], v[34:35] op_sel_hi:[0,1]
	v_pk_mul_f32 v[194:195], v[44:45], v[34:35]
	v_cvt_pk_bf16_f32 v34, v40, v41
	v_pk_mul_f32 v[38:39], v[42:43], v[38:39]
	s_waitcnt lgkmcnt(0)
	v_add_f32_dpp v40, v37, v37 quad_perm:[2,3,0,1] row_mask:0xf bank_mask:0xf
	v_cvt_pk_bf16_f32 v35, v186, v187
	v_cvt_pk_bf16_f32 v36, v38, v39
	v_cvt_pk_bf16_f32 v37, v194, v195
	ds_write_b128 v190, v[34:37]
	s_waitcnt lgkmcnt(1)
	v_add_f32_dpp v38, v40, v40 row_half_mirror row_mask:0xf bank_mask:0xf
	ds_read_b128 v[34:37], v191
	v_fmamk_f32 v38, v38, 0x3c800000, v171
	v_rsq_f32_e32 v186, v38
	s_lshl_b32 s8, s46, 12
	v_lshl_add_u64 v[38:39], v[180:181], 0, s[8:9]
	s_waitcnt lgkmcnt(0)
	global_store_dwordx4 v[38:39], v[34:37], off nt
	s_mov_b64 s[48:49], 0
	s_nop 0
	v_pk_mul_f32 v[34:35], v[186:187], v[200:201] op_sel_hi:[0,1]
	v_pk_mul_f32 v[38:39], v[54:55], v[34:35]
	v_pk_mul_f32 v[34:35], v[186:187], v[204:205] op_sel_hi:[0,1]
	v_pk_mul_f32 v[40:41], v[56:57], v[34:35]
	v_pk_mul_f32 v[34:35], v[186:187], v[188:189] op_sel_hi:[0,1]
	v_pk_mul_f32 v[36:37], v[186:187], v[196:197] op_sel_hi:[0,1]
	v_pk_mul_f32 v[34:35], v[50:51], v[34:35] op_sel:[0,1] op_sel_hi:[1,0]
	v_pk_mul_f32 v[36:37], v[52:53], v[36:37] op_sel:[0,1] op_sel_hi:[1,0]
